# strategy 6 (LDS bank conflicts): MLA K tile rows re-padded 208->224 bytes so the QK ds_read_b128 fragments are conflict-free per the lane-group model
# speedup vs baseline: 1.0055x; 1.0055x over previous
.LBB0_1348:
	s_or_b64 exec, exec, s[0:1]
	v_readlane_b32 s0, v246, 5
	s_and_b32 s3, s2, 7
	s_ashr_i32 s21, s0, 3
	s_ashr_i32 s20, s2, 3
	s_mul_i32 s0, s3, s21
	s_add_i32 s28, s0, s20
	s_cmpk_gt_i32 s28, 0x3ff
	s_waitcnt lgkmcnt(0)
	s_barrier
	v_readlane_b32 s1, v246, 6
	s_cbranch_scc1 .LBB0_1382
	v_mbcnt_hi_u32_b32 v164, -1, v163
	s_brev_b32 s4, 1
	v_and_b32_e32 v0, 64, v164
	s_mov_b32 s5, s4
	s_add_u32 s10, s64, 0xaa00000
	s_movk_i32 s24, 0xff80
	v_add_u32_e32 v166, 64, v0
	s_mov_b32 s6, s4
	s_mov_b32 s7, s4
	v_mov_b64_e32 v[0:1], s[4:5]
	s_mov_b32 s12, 0x3f803f80
	s_addc_u32 s11, s65, 0
	s_mov_b32 s17, 0
	v_mov_b32_e32 v145, 0
	s_movk_i32 s29, 0x600
	s_mov_b32 s30, 0x2aaaaaab
	s_movk_i32 s31, 0xff
	s_movk_i32 s33, 0x100
	s_movk_i32 s34, 0x70
	s_movk_i32 s35, 0xa0
	s_mov_b32 s25, -1
	v_xor_b32_e32 v165, 16, v164
	v_xor_b32_e32 v167, 32, v164
	v_mov_b64_e32 v[2:3], s[6:7]
	s_mov_b32 s13, s12
	s_mov_b32 s14, s12
	s_mov_b32 s15, s12
	s_mov_b32 s36, 0x41000000
	v_not_b32_e32 v168, 63
	s_mov_b32 s0, s28
	s_mov_b32 s37, 0
	s_branch .LBB0_1351

.LBB0_1361:
	s_or_b64 exec, exec, s[8:9]
	v_ashrrev_i32_e32 v120, 3, v36
	v_add_u32_e32 v38, s42, v120
	v_ashrrev_i32_e32 v39, 31, v38
	v_lshlrev_b64 v[38:39], 11, v[38:39]
	v_lshlrev_b32_e32 v41, 3, v36
	v_lshl_add_u64 v[38:39], s[86:87], 0, v[38:39]
	s_lshl_b32 s16, s26, 8
	v_and_b32_e32 v46, 56, v41
	v_lshl_add_u64 v[38:39], v[38:39], 0, s[16:17]
	v_lshlrev_b32_e32 v114, 1, v46
	v_mov_b32_e32 v115, v145
	v_lshl_add_u64 v[36:37], v[38:39], 0, v[114:115]
	global_load_dwordx4 v[36:39], v[36:37], off offset:128
	v_mul_lo_u32 v170, v118, s34
	v_lshlrev_b32_e32 v42, 4, v42
	v_lshlrev_b32_e32 v43, 3, v45
	v_ashrrev_i32_e32 v149, 31, v148
	v_ashrrev_i32_e32 v147, 31, v146
	v_lshl_add_u32 v121, v170, 1, v42
	v_lshlrev_b32_e32 v116, 3, v40
	v_mul_lo_u32 v171, v119, s34
	s_waitcnt vmcnt(1)
	ds_write_b128 v121, v[32:35]
	s_and_saveexec_b64 s[0:1], vcc
	s_xor_b64 s[0:1], exec, s[0:1]
	v_lshlrev_b32_e32 v116, 3, v40
	v_mul_lo_u32 v171, v119, s34
	s_andn2_saveexec_b64 s[0:1], s[0:1]
	v_lshlrev_b32_e32 v32, 4, v40
	v_lshl_add_u32 v32, v171, 1, v32
	ds_write_b128 v32, v[28:31]
	s_or_b64 exec, exec, s[0:1]
	s_lshl_b32 s16, s26, 7
	s_lshl_b32 s0, s16, 1
	s_add_u32 s0, s86, s0
	v_mul_lo_u32 v32, v120, s35
	s_addc_u32 s1, s87, 0
	s_or_b32 s46, s42, 64
	v_lshl_add_u32 v174, v46, 1, v32
	v_add_u32_e32 v32, s46, v118
	v_lshl_add_u64 v[150:151], v[112:113], 1, s[0:1]
	v_mov_b32_e32 v113, v145
	v_ashrrev_i32_e32 v33, 31, v32
	v_lshl_add_u64 v[152:153], v[112:113], 1, s[10:11]
	v_lshlrev_b64 v[34:35], 11, v[32:33]
	v_lshlrev_b64 v[32:33], 6, v[32:33]
	v_lshl_add_u64 v[32:33], v[152:153], 0, v[32:33]
	v_lshl_add_u64 v[34:35], v[150:151], 0, v[34:35]
	v_lshl_add_u64 v[32:33], v[32:33], 0, s[24:25]
	v_cndmask_b32_e64 v33, v33, v35, s[4:5]
	v_cndmask_b32_e64 v32, v32, v34, s[4:5]
	s_waitcnt vmcnt(0)
	ds_write_b128 v174, v[36:39] offset:28672
	s_waitcnt lgkmcnt(0)
	s_barrier
	global_load_dwordx4 v[32:35], v[32:33], off
	v_ashrrev_i32_e32 v117, 31, v116
	v_subrev_u32_e32 v144, 64, v116
	v_cmp_gt_i32_e64 s[8:9], 8, v40
	v_lshl_add_u64 v[154:155], v[144:145], 1, s[10:11]
	v_lshl_add_u64 v[156:157], v[116:117], 1, s[0:1]
	s_and_saveexec_b64 s[26:27], s[6:7]
	s_cbranch_execz .LBB0_1367
	v_add_u32_e32 v28, s46, v119
	v_ashrrev_i32_e32 v29, 31, v28
	v_lshlrev_b64 v[30:31], 11, v[28:29]
	v_lshlrev_b64 v[28:29], 6, v[28:29]
	v_lshl_add_u64 v[30:31], v[156:157], 0, v[30:31]
	v_lshl_add_u64 v[28:29], v[154:155], 0, v[28:29]
	v_cndmask_b32_e64 v29, v29, v31, s[8:9]
	v_cndmask_b32_e64 v28, v28, v30, s[8:9]
	global_load_dwordx4 v[28:31], v[28:29], off
.LBB0_1367:
	s_or_b64 exec, exec, s[26:27]
	v_mul_u32_u24_e32 v36, 0x70, v44
	v_lshlrev_b32_e32 v36, 1, v36
	v_lshl_add_u32 v175, v43, 1, v36
	ds_read_b128 v[36:39], v175
	ds_read_b128 v[46:49], v175 offset:64
	ds_read_b128 v[54:57], v175 offset:3584
	ds_read_b128 v[58:61], v175 offset:128
	ds_read_b128 v[66:69], v175 offset:7168
	ds_read_b128 v[70:73], v175 offset:7232
	v_add_u32_e32 v42, s46, v120
	s_waitcnt lgkmcnt(5)
	v_mfma_f32_16x16x32_bf16 v[50:53], v[36:39], v[20:23], v[0:3]
	v_ashrrev_i32_e32 v43, 31, v42
	v_lshlrev_b64 v[42:43], 11, v[42:43]
	v_lshl_add_u64 v[42:43], s[0:1], 0, v[42:43]
	v_mfma_f32_16x16x32_bf16 v[36:39], v[36:39], v[24:27], v[0:3]
	v_mov_b32_e32 v115, v145
	v_lshl_add_u64 v[42:43], v[42:43], 0, v[114:115]
	ds_read_b128 v[78:81], v175 offset:10752
	ds_read_b128 v[104:107], v175 offset:7296
	s_waitcnt lgkmcnt(3)
	v_mfma_f32_16x16x32_bf16 v[74:77], v[66:69], v[20:23], v[0:3]
	v_cmp_lt_i32_e32 vcc, v165, v166
	v_lshlrev_b32_e32 v169, 2, v45
	v_lshrrev_b32_e32 v40, 2, v44
	v_mfma_f32_16x16x32_bf16 v[66:69], v[66:69], v[24:27], v[0:3]
	v_or_b32_e32 v40, v169, v40
	v_mfma_f32_16x16x32_bf16 v[50:53], v[46:49], v[12:15], v[50:53]
	v_mfma_f32_16x16x32_bf16 v[36:39], v[46:49], v[16:19], v[36:39]
	ds_read_b128 v[46:49], v175 offset:3648
	ds_read_b128 v[92:95], v175 offset:3712
	ds_read_b128 v[126:129], v175 offset:10880
	s_waitcnt lgkmcnt(5)
	v_mfma_f32_16x16x32_bf16 v[108:111], v[70:73], v[12:15], v[74:77]
	v_mfma_f32_16x16x32_bf16 v[122:125], v[70:73], v[16:19], v[66:69]
	s_nop 1
	global_load_dwordx4 v[72:75], v[42:43], off offset:128
	v_cndmask_b32_e32 v42, v164, v165, vcc
	v_cmp_lt_i32_e32 vcc, v167, v166
	v_mfma_f32_16x16x32_bf16 v[62:65], v[54:57], v[20:23], v[0:3]
	v_lshlrev_b32_e32 v173, 2, v42
	v_mfma_f32_16x16x32_bf16 v[54:57], v[54:57], v[24:27], v[0:3]
	s_waitcnt lgkmcnt(2)
	v_mfma_f32_16x16x32_bf16 v[62:65], v[46:49], v[12:15], v[62:65]
	v_mfma_f32_16x16x32_bf16 v[46:49], v[46:49], v[16:19], v[54:57]
	s_nop 4
	ds_read_b128 v[54:57], v175 offset:10816
	v_mfma_f32_16x16x32_bf16 v[82:85], v[78:81], v[20:23], v[0:3]
	v_mfma_f32_16x16x32_bf16 v[78:81], v[78:81], v[24:27], v[0:3]
	v_mfma_f32_16x16x32_bf16 v[88:91], v[58:61], v[4:7], v[36:39]
	s_nop 2
	v_cndmask_b32_e32 v36, v164, v167, vcc
	v_lshlrev_b32_e32 v172, 2, v36
	v_mul_u32_u24_e32 v36, 0x50, v40
	v_lshlrev_b32_e32 v36, 1, v36
	s_waitcnt lgkmcnt(0)
	v_mfma_f32_16x16x32_bf16 v[130:133], v[54:57], v[12:15], v[82:85]
	v_and_or_b32 v176, v41, 24, v36
	v_mfma_f32_16x16x32_bf16 v[134:137], v[54:57], v[16:19], v[78:81]
	v_mfma_f32_16x16x32_bf16 v[96:99], v[58:61], v[8:11], v[50:53]
	v_mfma_f32_16x16x32_bf16 v[100:103], v[92:95], v[8:11], v[62:65]
	ds_read_b64_tr_b16 v[84:85], v176 offset:28672
	ds_read_b64_tr_b16 v[68:69], v176 offset:28704
	s_nop 0
	ds_read_b64_tr_b16 v[64:65], v176 offset:28736
	ds_read_b64_tr_b16 v[52:53], v176 offset:28768
	ds_read_b64_tr_b16 v[86:87], v176 offset:31232
	ds_read_b64_tr_b16 v[70:71], v176 offset:31264
	ds_read_b64_tr_b16 v[66:67], v176 offset:31296
	ds_read_b64_tr_b16 v[54:55], v176 offset:31328
	v_mfma_f32_16x16x32_bf16 v[92:95], v[92:95], v[4:7], v[46:49]
	s_nop 2
	ds_read_b64_tr_b16 v[48:49], v176 offset:33792
	ds_read_b64_tr_b16 v[44:45], v176 offset:33824
	ds_read_b64_tr_b16 v[40:41], v176 offset:33856
	ds_read_b64_tr_b16 v[36:37], v176 offset:33888
	ds_read_b64_tr_b16 v[50:51], v176 offset:36352
	ds_read_b64_tr_b16 v[46:47], v176 offset:36384
	ds_read_b64_tr_b16 v[42:43], v176 offset:36416
	ds_read_b64_tr_b16 v[38:39], v176 offset:36448
	v_mfma_f32_16x16x32_bf16 v[76:79], v[104:107], v[8:11], v[108:111]
	v_mfma_f32_16x16x32_bf16 v[56:59], v[104:107], v[4:7], v[122:125]
	v_mfma_f32_16x16x32_bf16 v[80:83], v[126:129], v[8:11], v[130:133]
	v_mfma_f32_16x16x32_bf16 v[60:63], v[126:129], v[4:7], v[134:137]
	v_max_f32_e32 v104, v97, v97
	v_max_f32_e32 v105, v96, v96
	v_max_f32_e32 v104, v105, v104
	v_max_f32_e32 v105, v99, v99
	v_max_f32_e32 v106, v98, v98
	v_max_f32_e32 v105, v106, v105
	v_max_f32_e32 v106, v103, v103
	v_max_f32_e32 v107, v102, v102
	v_max_f32_e32 v106, v107, v106
	v_max3_f32 v106, v100, v101, v106
	v_max3_f32 v104, v104, v105, v106
	v_max_f32_e32 v105, v79, v79
	v_max_f32_e32 v106, v78, v78
	v_max_f32_e32 v105, v106, v105
	v_max_f32_e32 v106, v83, v83
	v_max_f32_e32 v107, v82, v82
	v_max_f32_e32 v106, v107, v106
	v_max3_f32 v105, v76, v77, v105
	v_max3_f32 v106, v80, v81, v106
	v_max3_f32 v104, v104, v105, v106
	v_max_f32_e32 v106, v89, v89
	v_max_f32_e32 v107, v88, v88
	v_max_f32_e32 v106, v107, v106
	v_max_f32_e32 v107, v91, v91
	v_max_f32_e32 v108, v90, v90
	v_max_f32_e32 v107, v108, v107
	v_max_f32_e32 v108, v95, v95
	v_max_f32_e32 v109, v94, v94
	v_max_f32_e32 v108, v109, v108
	v_max3_f32 v108, v92, v93, v108
	v_max3_f32 v106, v106, v107, v108
	v_max_f32_e32 v107, v59, v59
	v_max_f32_e32 v108, v58, v58
	v_max_f32_e32 v107, v108, v107
	v_max_f32_e32 v108, v63, v63
	v_max_f32_e32 v109, v62, v62
	v_max_f32_e32 v108, v109, v108
	v_max3_f32 v107, v56, v57, v107
	v_max3_f32 v108, v60, v61, v108
	v_max3_f32 v106, v106, v107, v108
	ds_bpermute_b32 v105, v173, v104
	ds_bpermute_b32 v107, v173, v106
	s_cmp_eq_u64 exec, 0
	s_waitcnt lgkmcnt(1)
	v_max_f32_e32 v105, v105, v105
	s_waitcnt lgkmcnt(0)
	v_max_f32_e32 v107, v107, v107
	v_max_f32_e32 v104, v104, v105
	v_max_f32_e32 v106, v106, v107
	ds_bpermute_b32 v105, v172, v104
	ds_bpermute_b32 v107, v172, v106
	s_cbranch_scc1 .LBB0_1369
	s_waitcnt lgkmcnt(0)
	v_max_f32_e32 v107, v107, v107
	v_max_f32_e32 v106, v106, v106
	v_max_f32_e32 v105, v105, v105
	v_max_f32_e32 v104, v104, v104
	v_max_f32_e32 v106, v106, v107
	v_max_f32_e32 v107, v104, v105
	v_exp_f32_e64 v104, -v107
	v_sub_f32_e32 v96, v96, v107
	v_sub_f32_e32 v97, v97, v107
	v_sub_f32_e32 v98, v98, v107
	v_mul_f32_e32 v108, 0, v104
	v_exp_f32_e64 v104, -v106
	v_sub_f32_e32 v99, v99, v107
	v_sub_f32_e32 v100, v100, v107
	v_sub_f32_e32 v101, v101, v107
	v_sub_f32_e32 v102, v102, v107
	v_sub_f32_e32 v103, v103, v107
	v_sub_f32_e32 v76, v76, v107
	v_sub_f32_e32 v77, v77, v107
	v_sub_f32_e32 v78, v78, v107
	v_sub_f32_e32 v79, v79, v107
	v_sub_f32_e32 v80, v80, v107
	v_sub_f32_e32 v81, v81, v107
	v_sub_f32_e32 v82, v82, v107
	v_sub_f32_e32 v83, v83, v107
	v_pk_add_f32 v[158:159], v[106:107], 0 op_sel_hi:[1,0]
	v_sub_f32_e32 v88, v88, v106
	v_sub_f32_e32 v89, v89, v106
	v_sub_f32_e32 v90, v90, v106
	v_sub_f32_e32 v91, v91, v106
	v_sub_f32_e32 v92, v92, v106
	v_sub_f32_e32 v93, v93, v106
	v_sub_f32_e32 v94, v94, v106
	v_sub_f32_e32 v95, v95, v106
	v_sub_f32_e32 v56, v56, v106
	v_sub_f32_e32 v57, v57, v106
	v_sub_f32_e32 v58, v58, v106
	v_sub_f32_e32 v59, v59, v106
	v_sub_f32_e32 v60, v60, v106
	v_sub_f32_e32 v61, v61, v106
	v_sub_f32_e32 v62, v62, v106
	v_sub_f32_e32 v63, v63, v106
	v_mul_f32_e32 v104, 0, v104
	s_branch .LBB0_1370

.LBB0_1370:
	v_exp_f32_e32 v96, v96
	v_exp_f32_e32 v97, v97
	v_exp_f32_e32 v98, v98
	v_exp_f32_e32 v99, v99
	v_exp_f32_e32 v100, v100
	v_exp_f32_e32 v101, v101
	v_exp_f32_e32 v102, v102
	v_exp_f32_e32 v103, v103
	v_cvt_pk_bf16_f32 v96, v96, v97
	v_cvt_pk_bf16_f32 v97, v98, v99
	v_cvt_pk_bf16_f32 v98, v100, v101
	v_cvt_pk_bf16_f32 v99, v102, v103
	v_exp_f32_e32 v88, v88
	v_exp_f32_e32 v89, v89
	v_exp_f32_e32 v90, v90
	v_exp_f32_e32 v91, v91
	v_exp_f32_e32 v100, v92
	v_exp_f32_e32 v101, v93
	v_exp_f32_e32 v102, v94
	v_exp_f32_e32 v103, v95
	v_mov_b64_e32 v[136:137], s[14:15]
	v_mov_b64_e32 v[134:135], s[12:13]
	v_mov_b32_e32 v109, v108
	v_mov_b32_e32 v110, v108
	v_mov_b32_e32 v111, v108
	s_waitcnt lgkmcnt(1)
	v_mov_b32_e32 v105, v104
	v_mov_b32_e32 v106, v104
	s_waitcnt lgkmcnt(0)
	v_mov_b32_e32 v107, v104
	v_cvt_pk_bf16_f32 v88, v88, v89
	v_cvt_pk_bf16_f32 v89, v90, v91
	v_cvt_pk_bf16_f32 v90, v100, v101
	v_cvt_pk_bf16_f32 v91, v102, v103
	v_mfma_f32_16x16x32_bf16 v[100:103], v[68:71], v[96:99], v[108:111]
	v_exp_f32_e32 v113, v76
	v_exp_f32_e32 v115, v81
	v_exp_f32_e32 v117, v82
	v_mfma_f32_16x16x32_bf16 v[122:125], v[68:71], v[88:91], v[104:107]
	v_exp_f32_e32 v68, v77
	v_exp_f32_e32 v69, v78
	v_exp_f32_e32 v70, v79
	v_mfma_f32_16x16x32_bf16 v[76:79], v[64:67], v[96:99], v[108:111]
	v_exp_f32_e32 v71, v80
	v_cvt_pk_bf16_f32 v80, v113, v68
	v_cvt_pk_bf16_f32 v81, v69, v70
	v_mfma_f32_16x16x32_bf16 v[126:129], v[64:67], v[88:91], v[104:107]
	v_exp_f32_e32 v64, v83
	v_cvt_pk_bf16_f32 v82, v71, v115
	s_waitcnt vmcnt(1)
	ds_write_b128 v121, v[32:35] offset:14336
	v_mfma_f32_16x16x32_bf16 v[130:133], v[52:55], v[96:99], v[108:111]
	v_cvt_pk_bf16_f32 v83, v117, v64
	v_lshlrev_b32_e32 v144, 1, v116
	v_mfma_f32_16x16x32_bf16 v[138:141], v[52:55], v[88:91], v[104:107]
	v_exp_f32_e32 v52, v56
	v_exp_f32_e32 v53, v57
	v_exp_f32_e32 v54, v58
	v_exp_f32_e32 v55, v59
	v_exp_f32_e32 v56, v60
	v_exp_f32_e32 v57, v61
	v_exp_f32_e32 v58, v62
	v_exp_f32_e32 v59, v63
	v_mfma_f32_16x16x32_bf16 v[92:95], v[84:87], v[96:99], v[108:111]
	v_mfma_f32_16x16x32_bf16 v[84:87], v[84:87], v[88:91], v[104:107]
	v_mfma_f32_16x16x32_bf16 v[96:99], v[134:137], v[96:99], v[108:111]
	v_mfma_f32_16x16x32_bf16 v[88:91], v[134:137], v[88:91], v[104:107]
	s_nop 2
	v_cvt_pk_bf16_f32 v104, v52, v53
	v_cvt_pk_bf16_f32 v105, v54, v55
	v_cvt_pk_bf16_f32 v106, v56, v57
	v_cvt_pk_bf16_f32 v107, v58, v59
	v_mfma_f32_16x16x32_bf16 v[68:71], v[48:51], v[80:83], v[92:95]
	s_nop 0
	v_mfma_f32_16x16x32_bf16 v[64:67], v[48:51], v[104:107], v[84:87]
	v_mfma_f32_16x16x32_bf16 v[60:63], v[44:47], v[80:83], v[100:103]
	v_mfma_f32_16x16x32_bf16 v[56:59], v[44:47], v[104:107], v[122:125]
	v_mfma_f32_16x16x32_bf16 v[52:55], v[40:43], v[80:83], v[76:79]
	v_mfma_f32_16x16x32_bf16 v[48:51], v[40:43], v[104:107], v[126:129]
	v_mfma_f32_16x16x32_bf16 v[44:47], v[36:39], v[80:83], v[130:133]
	v_mfma_f32_16x16x32_bf16 v[40:43], v[36:39], v[104:107], v[138:141]
	v_mfma_f32_16x16x32_bf16 v[36:39], v[134:137], v[80:83], v[96:99]
	v_mfma_f32_16x16x32_bf16 v[32:35], v[134:137], v[104:107], v[88:91]
	s_and_saveexec_b64 s[26:27], s[6:7]
	v_lshl_add_u32 v76, v171, 1, v144
	ds_write_b128 v76, v[28:31] offset:14336
	s_or_b64 exec, exec, s[26:27]
	s_lshl_b32 s26, s43, 8
	v_mov_b32_e32 v115, v145
	s_addk_i32 s26, 0x7800
	s_mov_b32 s27, 1
	v_lshl_add_u64 v[160:161], s[0:1], 0, v[114:115]
	v_add_u32_e32 v177, 0x80, v119
	v_add_u32_e32 v178, 0x80, v120
	v_add_u32_e32 v179, 0x80, v118
	v_lshlrev_b32_e32 v180, 1, v112
	v_mov_b32_e32 v203, 0
	v_mov_b32_e32 v210, v179
	v_mov_b32_e32 v211, 0
	v_mov_b32_e32 v214, 0x800
	v_lshlrev_b64 v[212:213], 11, v[210:211]
	v_lshlrev_b64 v[210:211], 6, v[210:211]
	v_lshl_add_u64 v[210:211], v[152:153], 0, v[210:211]
	v_lshl_add_u64 v[212:213], v[150:151], 0, v[212:213]
	v_lshl_add_u64 v[210:211], v[210:211], 0, s[24:25]
	v_cndmask_b32_e64 v205, v211, v213, s[4:5]
	v_cndmask_b32_e64 v204, v210, v212, s[4:5]
	v_mov_b32_e32 v206, 64
	v_cndmask_b32_e64 v206, v206, v214, s[4:5]
	v_mov_b32_e32 v210, v177
	v_mov_b32_e32 v211, 0
	v_lshlrev_b64 v[212:213], 11, v[210:211]
	v_lshlrev_b64 v[210:211], 6, v[210:211]
	v_lshl_add_u64 v[212:213], v[156:157], 0, v[212:213]
	v_lshl_add_u64 v[210:211], v[154:155], 0, v[210:211]
	v_cndmask_b32_e64 v209, v211, v213, s[8:9]
	v_cndmask_b32_e64 v208, v210, v212, s[8:9]
	v_mov_b32_e32 v207, 64
	v_cndmask_b32_e64 v207, v207, v214, s[8:9]
	v_mov_b32_e32 v210, v178
	v_mov_b32_e32 v211, 0
	v_lshlrev_b64 v[210:211], 11, v[210:211]
	v_lshl_add_u64 v[216:217], v[160:161], 0, v[210:211]
	v_xor_b32_e32 v218, 0x80000000, v159
	v_xor_b32_e32 v222, 0x80000000, v158
	v_mov_b32_e32 v219, v218
	v_mov_b32_e32 v220, v218
	v_mov_b32_e32 v221, v218
	v_mov_b32_e32 v223, v222
	v_mov_b32_e32 v224, v222
	v_mov_b32_e32 v225, v222
	v_mov_b64_e32 v[228:229], s[12:13]
	v_mov_b64_e32 v[230:231], s[14:15]
	s_waitcnt vmcnt(0)
	ds_write_b128 v174, v[72:75] offset:38912
	s_waitcnt lgkmcnt(0)
	s_barrier
	s_branch .LBB0_1374
.LBB0_1373:
	s_or_b64 exec, exec, s[0:1]
	s_add_i32 s27, s27, 1
	s_mulk_i32 s43, 0x2800
	v_add_u32_e32 v72, s43, v174
	s_cmp_lg_u32 s27, 35
	s_waitcnt vmcnt(0)
	ds_write_b128 v72, v[232:235] offset:28672
	s_waitcnt lgkmcnt(0)
	s_barrier
	s_cbranch_scc0 .LBB0_1380
.LBB0_1374:
	s_and_b32 s99, s27, 1
	s_mul_i32 s99, s99, 0x3800
	v_add_u32_e32 v124, s99, v175
	ds_read_b128 v[76:79], v124
	ds_read_b128 v[88:91], v124 offset:64
	s_cmp_lt_u32 s27, 31
	s_cselect_b32 s43, s42, s26
	s_lshl_b32 s98, s27, 6
	s_add_i32 s98, s98, s43
	s_addk_i32 s98, 0xffc0
	s_lshl_b32 s100, s98, 11
	s_mov_b32 s101, 0
	v_mul_u32_u24_e32 v202, s98, v206
	v_lshl_add_u64 v[72:73], v[204:205], 0, v[202:203]
	global_load_dwordx4 v[72:75], v[72:73], off
	s_and_saveexec_b64 s[0:1], s[6:7]
	s_cbranch_execz .LBB0_1376
	v_mul_u32_u24_e32 v202, s98, v207
	v_lshl_add_u64 v[28:29], v[208:209], 0, v[202:203]
	global_load_dwordx4 v[28:31], v[28:29], off
.LBB0_1376:
	s_or_b64 exec, exec, s[0:1]
	v_lshl_add_u64 v[232:233], v[216:217], 0, s[100:101]
	global_load_dwordx4 v[232:235], v[232:233], off offset:128
	s_and_b32 s0, s27, 1
	s_mul_i32 s1, s0, 0x3800
	s_waitcnt lgkmcnt(1)
	v_mfma_f32_16x16x32_bf16 v[92:95], v[76:79], v[20:23], v[218:221]
	ds_read_b128 v[96:99], v124 offset:3584
	ds_read_b128 v[100:103], v124 offset:128
	ds_read_b128 v[108:111], v124 offset:7168
	ds_read_b128 v[112:115], v124 offset:7232
	ds_read_b128 v[120:123], v124 offset:10752
	ds_read_b128 v[182:185], v124 offset:7296
	v_mfma_f32_16x16x32_bf16 v[76:79], v[76:79], v[24:27], v[222:225]
	s_mul_i32 s1, s0, 0x2800
	s_waitcnt lgkmcnt(5)
	v_mfma_f32_16x16x32_bf16 v[104:107], v[96:99], v[20:23], v[218:221]
	v_mfma_f32_16x16x32_bf16 v[96:99], v[96:99], v[24:27], v[222:225]
	s_waitcnt lgkmcnt(3)
	v_mfma_f32_16x16x32_bf16 v[116:119], v[108:111], v[20:23], v[218:221]
	v_mfma_f32_16x16x32_bf16 v[108:111], v[108:111], v[24:27], v[222:225]
	s_waitcnt lgkmcnt(1)
	v_mfma_f32_16x16x32_bf16 v[80:83], v[120:123], v[20:23], v[218:221]
	v_mfma_f32_16x16x32_bf16 v[84:87], v[120:123], v[24:27], v[222:225]
	v_mfma_f32_16x16x32_bf16 v[92:95], v[88:91], v[12:15], v[92:95]
	v_mfma_f32_16x16x32_bf16 v[76:79], v[88:91], v[16:19], v[76:79]
	ds_read_b128 v[88:91], v124 offset:3648
	ds_read_b128 v[120:123], v124 offset:3712
	s_waitcnt lgkmcnt(1)
	v_mfma_f32_16x16x32_bf16 v[104:107], v[88:91], v[12:15], v[104:107]
	v_mfma_f32_16x16x32_bf16 v[88:91], v[88:91], v[16:19], v[96:99]
	s_nop 2
	ds_read_b128 v[96:99], v124 offset:10816
	ds_read_b128 v[190:193], v124 offset:10880
	s_waitcnt lgkmcnt(1)
	v_mfma_f32_16x16x32_bf16 v[194:197], v[96:99], v[12:15], v[80:83]
	s_nop 2
	v_mfma_f32_16x16x32_bf16 v[128:131], v[100:103], v[4:7], v[76:79]
	v_add_u32_e32 v82, s1, v176
	s_nop 1
	v_mfma_f32_16x16x32_bf16 v[116:119], v[112:115], v[12:15], v[116:119]
	v_mfma_f32_16x16x32_bf16 v[186:189], v[112:115], v[16:19], v[108:111]
	v_mfma_f32_16x16x32_bf16 v[198:201], v[96:99], v[16:19], v[84:87]
	ds_read_b64_tr_b16 v[124:125], v82 offset:28672
	ds_read_b64_tr_b16 v[112:113], v82 offset:28704
	ds_read_b64_tr_b16 v[108:109], v82 offset:28736
	ds_read_b64_tr_b16 v[96:97], v82 offset:28768
	ds_read_b64_tr_b16 v[126:127], v82 offset:31232
	ds_read_b64_tr_b16 v[114:115], v82 offset:31264
	ds_read_b64_tr_b16 v[110:111], v82 offset:31296
	ds_read_b64_tr_b16 v[98:99], v82 offset:31328
	v_mfma_f32_16x16x32_bf16 v[136:139], v[100:103], v[8:11], v[92:95]
	v_mfma_f32_16x16x32_bf16 v[132:135], v[120:123], v[4:7], v[88:91]
	s_nop 1
	ds_read_b64_tr_b16 v[92:93], v82 offset:33792
	ds_read_b64_tr_b16 v[88:89], v82 offset:33824
	ds_read_b64_tr_b16 v[84:85], v82 offset:33856
	ds_read_b64_tr_b16 v[80:81], v82 offset:33888
	ds_read_b64_tr_b16 v[94:95], v82 offset:36352
	ds_read_b64_tr_b16 v[90:91], v82 offset:36384
	ds_read_b64_tr_b16 v[86:87], v82 offset:36416
	ds_read_b64_tr_b16 v[82:83], v82 offset:36448
	v_mfma_f32_16x16x32_bf16 v[140:143], v[120:123], v[8:11], v[104:107]
	v_mfma_f32_16x16x32_bf16 v[116:119], v[182:185], v[8:11], v[116:119]
	v_mfma_f32_16x16x32_bf16 v[100:103], v[182:185], v[4:7], v[186:189]
	s_waitcnt lgkmcnt(14)
	v_mfma_f32_16x16x32_bf16 v[120:123], v[190:193], v[8:11], v[194:197]
	v_mfma_f32_16x16x32_bf16 v[104:107], v[190:193], v[4:7], v[198:201]
	v_max3_f32 v181, v136, v137, v138
	v_max3_f32 v183, v128, v129, v130
	v_max3_f32 v184, v131, v132, v133
	v_max3_f32 v181, v181, v139, v140
	v_max3_f32 v183, v183, v134, v135
	v_max3_f32 v181, v181, v141, v142
	v_max3_f32 v182, v143, v116, v117
	v_max3_f32 v184, v184, v100, v101
	v_max3_f32 v182, v182, v118, v119
	v_max3_f32 v184, v184, v102, v103
	v_max3_f32 v181, v181, v120, v121
	v_max3_f32 v182, v182, v122, v123
	v_max3_f32 v183, v183, v104, v105
	v_max3_f32 v184, v184, v106, v107
	v_max_f32_e32 v181, v181, v182
	v_max_f32_e32 v183, v183, v184
	v_max_f32_e32 v184, v181, v183
	v_cmp_lt_f32_e32 vcc, s36, v184
	s_cbranch_vccz .LBB0_1378
	v_mov_b32_e32 v182, v181
	v_mov_b32_e32 v184, v183
	s_nop 1
	v_permlane16_swap_b32_e32 v181, v182
	v_permlane16_swap_b32_e32 v183, v184
	v_max_f32_e32 v181, v181, v182
	v_max_f32_e32 v183, v183, v184
	v_mov_b32_e32 v182, v181
	v_mov_b32_e32 v184, v183
	s_nop 1
	v_permlane32_swap_b32_e32 v181, v182
	v_permlane32_swap_b32_e32 v183, v184
	v_max_f32_e32 v182, v181, v182
	v_max_f32_e32 v181, v183, v184
	v_max_f32_e32 v182, v182, v182
	v_max_f32_e32 v183, 0, v182
	v_exp_f32_e64 v182, -v183
	v_max_f32_e32 v181, v181, v181
	v_sub_f32_e32 v136, v136, v183
	v_sub_f32_e32 v137, v137, v183
	v_pk_mul_f32 v[70:71], v[70:71], v[182:183] op_sel_hi:[1,0]
	v_pk_mul_f32 v[68:69], v[68:69], v[182:183] op_sel_hi:[1,0]
	v_pk_mul_f32 v[62:63], v[62:63], v[182:183] op_sel_hi:[1,0]
	v_pk_mul_f32 v[60:61], v[60:61], v[182:183] op_sel_hi:[1,0]
	v_pk_mul_f32 v[54:55], v[54:55], v[182:183] op_sel_hi:[1,0]
	v_pk_mul_f32 v[52:53], v[52:53], v[182:183] op_sel_hi:[1,0]
	v_pk_mul_f32 v[46:47], v[46:47], v[182:183] op_sel_hi:[1,0]
	v_pk_mul_f32 v[44:45], v[44:45], v[182:183] op_sel_hi:[1,0]
	v_pk_mul_f32 v[38:39], v[38:39], v[182:183] op_sel_hi:[1,0]
	v_pk_mul_f32 v[36:37], v[36:37], v[182:183] op_sel_hi:[1,0]
	v_max_f32_e32 v182, 0, v181
	v_exp_f32_e64 v184, -v182
	v_sub_f32_e32 v138, v138, v183
	v_sub_f32_e32 v139, v139, v183
	v_sub_f32_e32 v140, v140, v183
	v_sub_f32_e32 v141, v141, v183
	v_sub_f32_e32 v142, v142, v183
	v_sub_f32_e32 v143, v143, v183
	v_sub_f32_e32 v116, v116, v183
	v_sub_f32_e32 v117, v117, v183
	v_sub_f32_e32 v118, v118, v183
	v_sub_f32_e32 v119, v119, v183
	v_sub_f32_e32 v120, v120, v183
	v_sub_f32_e32 v121, v121, v183
	v_sub_f32_e32 v122, v122, v183
	v_sub_f32_e32 v123, v123, v183
	v_pk_add_f32 v[158:159], v[158:159], v[182:183]
	v_xor_b32_e32 v218, 0x80000000, v159
	v_xor_b32_e32 v222, 0x80000000, v158
	v_mov_b32_e32 v219, v218
	v_mov_b32_e32 v220, v218
	v_mov_b32_e32 v221, v218
	v_mov_b32_e32 v223, v222
	v_mov_b32_e32 v224, v222
	v_mov_b32_e32 v225, v222
	v_sub_f32_e32 v128, v128, v182
	v_sub_f32_e32 v129, v129, v182
	v_sub_f32_e32 v130, v130, v182
	v_sub_f32_e32 v131, v131, v182
	v_sub_f32_e32 v132, v132, v182
	v_sub_f32_e32 v133, v133, v182
	v_sub_f32_e32 v134, v134, v182
	v_sub_f32_e32 v135, v135, v182
	v_sub_f32_e32 v100, v100, v182
	v_sub_f32_e32 v101, v101, v182
	v_sub_f32_e32 v102, v102, v182
	v_sub_f32_e32 v103, v103, v182
	v_sub_f32_e32 v104, v104, v182
	v_sub_f32_e32 v105, v105, v182
	v_sub_f32_e32 v106, v106, v182
	v_sub_f32_e32 v107, v107, v182
	v_pk_mul_f32 v[66:67], v[66:67], v[184:185] op_sel_hi:[1,0]
	v_pk_mul_f32 v[64:65], v[64:65], v[184:185] op_sel_hi:[1,0]
	v_pk_mul_f32 v[58:59], v[58:59], v[184:185] op_sel_hi:[1,0]
	v_pk_mul_f32 v[56:57], v[56:57], v[184:185] op_sel_hi:[1,0]
	v_pk_mul_f32 v[50:51], v[50:51], v[184:185] op_sel_hi:[1,0]
	v_pk_mul_f32 v[48:49], v[48:49], v[184:185] op_sel_hi:[1,0]
	v_pk_mul_f32 v[42:43], v[42:43], v[184:185] op_sel_hi:[1,0]
	v_pk_mul_f32 v[40:41], v[40:41], v[184:185] op_sel_hi:[1,0]
	v_pk_mul_f32 v[34:35], v[34:35], v[184:185] op_sel_hi:[1,0]
	v_pk_mul_f32 v[32:33], v[32:33], v[184:185] op_sel_hi:[1,0]
.LBB0_1378:
	v_exp_f32_e32 v136, v136
	v_exp_f32_e32 v137, v137
	v_exp_f32_e32 v138, v138
	v_exp_f32_e32 v139, v139
	v_exp_f32_e32 v140, v140
	v_exp_f32_e32 v141, v141
	v_exp_f32_e32 v142, v142
	v_exp_f32_e32 v143, v143
	v_exp_f32_e32 v128, v128
	v_exp_f32_e32 v129, v129
	v_exp_f32_e32 v130, v130
	v_exp_f32_e32 v131, v131
	v_exp_f32_e32 v132, v132
	v_exp_f32_e32 v133, v133
	v_exp_f32_e32 v134, v134
	v_exp_f32_e32 v135, v135
	v_cvt_pk_bf16_f32 v136, v136, v137
	v_cvt_pk_bf16_f32 v137, v138, v139
	v_cvt_pk_bf16_f32 v138, v140, v141
	v_cvt_pk_bf16_f32 v139, v142, v143
	v_cvt_pk_bf16_f32 v128, v128, v129
	v_cvt_pk_bf16_f32 v129, v130, v131
	v_cvt_pk_bf16_f32 v130, v132, v133
	v_cvt_pk_bf16_f32 v131, v134, v135
	s_waitcnt lgkmcnt(0)
	v_mfma_f32_16x16x32_bf16 v[60:63], v[112:115], v[136:139], v[60:63]
	v_exp_f32_e32 v116, v116
	s_xor_b32 s43, s0, 1
	s_mul_i32 s46, s43, 0x3800
	v_mfma_f32_16x16x32_bf16 v[56:59], v[112:115], v[128:131], v[56:59]
	v_exp_f32_e32 v112, v117
	v_exp_f32_e32 v113, v118
	v_exp_f32_e32 v114, v119
	v_exp_f32_e32 v115, v120
	v_exp_f32_e32 v117, v121
	v_mfma_f32_16x16x32_bf16 v[52:55], v[108:111], v[136:139], v[52:55]
	v_exp_f32_e32 v118, v122
	v_mfma_f32_16x16x32_bf16 v[48:51], v[108:111], v[128:131], v[48:51]
	v_cvt_pk_bf16_f32 v108, v116, v112
	v_cvt_pk_bf16_f32 v109, v113, v114
	v_cvt_pk_bf16_f32 v110, v115, v117
	v_exp_f32_e32 v111, v123
	v_mfma_f32_16x16x32_bf16 v[44:47], v[96:99], v[136:139], v[44:47]
	v_cvt_pk_bf16_f32 v111, v118, v111
	v_mfma_f32_16x16x32_bf16 v[40:43], v[96:99], v[128:131], v[40:43]
	v_exp_f32_e32 v96, v100
	v_exp_f32_e32 v97, v101
	v_exp_f32_e32 v98, v102
	v_exp_f32_e32 v99, v103
	v_exp_f32_e32 v100, v104
	v_exp_f32_e32 v101, v105
	v_exp_f32_e32 v102, v106
	v_exp_f32_e32 v103, v107
	v_mfma_f32_16x16x32_bf16 v[68:71], v[124:127], v[136:139], v[68:71]
	v_cvt_pk_bf16_f32 v96, v96, v97
	v_cvt_pk_bf16_f32 v97, v98, v99
	v_cvt_pk_bf16_f32 v98, v100, v101
	v_mfma_f32_16x16x32_bf16 v[64:67], v[124:127], v[128:131], v[64:67]
	v_cvt_pk_bf16_f32 v99, v102, v103
	v_mfma_f32_16x16x32_bf16 v[36:39], v[228:231], v[136:139], v[36:39]
	v_mfma_f32_16x16x32_bf16 v[32:35], v[228:231], v[128:131], v[32:35]
	v_mfma_f32_16x16x32_bf16 v[68:71], v[92:95], v[108:111], v[68:71]
	v_mfma_f32_16x16x32_bf16 v[64:67], v[92:95], v[96:99], v[64:67]
	v_mfma_f32_16x16x32_bf16 v[60:63], v[88:91], v[108:111], v[60:63]
	v_mfma_f32_16x16x32_bf16 v[56:59], v[88:91], v[96:99], v[56:59]
	v_mfma_f32_16x16x32_bf16 v[52:55], v[84:87], v[108:111], v[52:55]
	v_mfma_f32_16x16x32_bf16 v[48:51], v[84:87], v[96:99], v[48:51]
	v_mfma_f32_16x16x32_bf16 v[44:47], v[80:83], v[108:111], v[44:47]
	v_mfma_f32_16x16x32_bf16 v[40:43], v[80:83], v[96:99], v[40:43]
	v_lshlrev_b32_e32 v80, 1, v170
	v_add3_u32 v80, s46, v80, v180
	s_waitcnt vmcnt(1)
	ds_write_b128 v80, v[72:75]
	v_mfma_f32_16x16x32_bf16 v[36:39], v[228:231], v[108:111], v[36:39]
	v_mfma_f32_16x16x32_bf16 v[32:35], v[228:231], v[96:99], v[32:35]
	s_and_saveexec_b64 s[0:1], s[6:7]
	s_cbranch_execz .LBB0_1373
	v_lshlrev_b32_e32 v72, 1, v171
	v_add3_u32 v72, s46, v72, v144
	ds_write_b128 v72, v[28:31]
	s_branch .LBB0_1373
.LBB0_1380:
	ds_read_b128 v[28:31], v175 offset:14336
	ds_read_b128 v[80:83], v175 offset:14400
	v_xor_b32_e32 v72, 0x80000000, v159
	v_xor_b32_e32 v76, 0x80000000, v158
	v_mov_b32_e32 v73, v72
	v_mov_b32_e32 v74, v72
	v_mov_b32_e32 v75, v72
	v_mov_b32_e32 v77, v76
	v_mov_b32_e32 v78, v76
	v_mov_b32_e32 v79, v76
	s_waitcnt lgkmcnt(1)
	v_mfma_f32_16x16x32_bf16 v[84:87], v[28:31], v[20:23], v[72:75]
	ds_read_b128 v[88:91], v175 offset:17920
	ds_read_b128 v[92:95], v175 offset:14464
	ds_read_b128 v[100:103], v175 offset:21504
	ds_read_b128 v[104:107], v175 offset:21568
	ds_read_b128 v[112:115], v175 offset:25088
	ds_read_b128 v[116:119], v175 offset:21632
	v_mfma_f32_16x16x32_bf16 v[28:31], v[28:31], v[24:27], v[76:79]
	s_waitcnt lgkmcnt(5)
	v_mfma_f32_16x16x32_bf16 v[96:99], v[88:91], v[20:23], v[72:75]
	v_mfma_f32_16x16x32_bf16 v[88:91], v[88:91], v[24:27], v[76:79]
	s_waitcnt lgkmcnt(3)
	v_mfma_f32_16x16x32_bf16 v[108:111], v[100:103], v[20:23], v[72:75]
	v_mfma_f32_16x16x32_bf16 v[100:103], v[100:103], v[24:27], v[76:79]
	s_waitcnt lgkmcnt(1)
	v_mfma_f32_16x16x32_bf16 v[20:23], v[112:115], v[20:23], v[72:75]
	v_mfma_f32_16x16x32_bf16 v[24:27], v[112:115], v[24:27], v[76:79]
	v_mfma_f32_16x16x32_bf16 v[72:75], v[80:83], v[12:15], v[84:87]
	v_mfma_f32_16x16x32_bf16 v[28:31], v[80:83], v[16:19], v[28:31]
	s_nop 0
	ds_read_b128 v[76:79], v175 offset:17984
	ds_read_b128 v[80:83], v175 offset:18048
	s_waitcnt lgkmcnt(1)
	v_mfma_f32_16x16x32_bf16 v[84:87], v[76:79], v[12:15], v[96:99]
	v_mfma_f32_16x16x32_bf16 v[76:79], v[76:79], v[16:19], v[88:91]
	s_nop 2
	ds_read_b128 v[88:91], v175 offset:25152
	ds_read_b128 v[120:123], v175 offset:25216
	v_mfma_f32_16x16x32_bf16 v[108:111], v[104:107], v[12:15], v[108:111]
	v_mfma_f32_16x16x32_bf16 v[112:115], v[104:107], v[16:19], v[100:103]
	s_waitcnt lgkmcnt(1)
	v_mfma_f32_16x16x32_bf16 v[124:127], v[88:91], v[12:15], v[20:23]
	v_mfma_f32_16x16x32_bf16 v[128:131], v[88:91], v[16:19], v[24:27]
	v_mfma_f32_16x16x32_bf16 v[104:107], v[92:95], v[8:11], v[72:75]
	v_mfma_f32_16x16x32_bf16 v[96:99], v[92:95], v[4:7], v[28:31]
	v_mfma_f32_16x16x32_bf16 v[100:103], v[80:83], v[8:11], v[84:87]
	v_mfma_f32_16x16x32_bf16 v[92:95], v[80:83], v[4:7], v[76:79]
	ds_read_b64_tr_b16 v[88:89], v176 offset:38912
	ds_read_b64_tr_b16 v[80:81], v176 offset:38944
	s_nop 0
	ds_read_b64_tr_b16 v[76:77], v176 offset:38976
	ds_read_b64_tr_b16 v[28:29], v176 offset:39008
	ds_read_b64_tr_b16 v[90:91], v176 offset:41472
	ds_read_b64_tr_b16 v[82:83], v176 offset:41504
	ds_read_b64_tr_b16 v[78:79], v176 offset:41536
	ds_read_b64_tr_b16 v[30:31], v176 offset:41568
	ds_read_b64_tr_b16 v[24:25], v176 offset:44032
	ds_read_b64_tr_b16 v[20:21], v176 offset:44064
	ds_read_b64_tr_b16 v[16:17], v176 offset:44096
	ds_read_b64_tr_b16 v[12:13], v176 offset:44128
	ds_read_b64_tr_b16 v[26:27], v176 offset:46592
	ds_read_b64_tr_b16 v[22:23], v176 offset:46624
	ds_read_b64_tr_b16 v[18:19], v176 offset:46656
	ds_read_b64_tr_b16 v[14:15], v176 offset:46688
	v_mfma_f32_16x16x32_bf16 v[84:87], v[116:119], v[8:11], v[108:111]
	v_mfma_f32_16x16x32_bf16 v[72:75], v[116:119], v[4:7], v[112:115]
	s_waitcnt lgkmcnt(14)
	v_mfma_f32_16x16x32_bf16 v[8:11], v[120:123], v[8:11], v[124:127]
	v_mfma_f32_16x16x32_bf16 v[4:7], v[120:123], v[4:7], v[128:131]
	v_max_f32_e32 v108, v105, v105
	v_max_f32_e32 v109, v104, v104
	v_max_f32_e32 v108, v109, v108
	v_max_f32_e32 v109, v107, v107
	v_max_f32_e32 v110, v106, v106
	v_max_f32_e32 v109, v110, v109
	v_max_f32_e32 v110, v103, v103
	v_max_f32_e32 v111, v102, v102
	v_max_f32_e32 v110, v111, v110
	v_max3_f32 v110, v100, v101, v110
	v_max3_f32 v108, v108, v109, v110
	v_max_f32_e32 v109, v87, v87
	v_max_f32_e32 v110, v86, v86
	v_max_f32_e32 v109, v110, v109
	v_max_f32_e32 v110, v11, v11
	v_max_f32_e32 v111, v10, v10
	v_max_f32_e32 v110, v111, v110
	v_max3_f32 v109, v84, v85, v109
	v_max3_f32 v110, v8, v9, v110
	v_max3_f32 v108, v108, v109, v110
	v_max_f32_e32 v110, v97, v97
	v_max_f32_e32 v111, v96, v96
	v_max_f32_e32 v110, v111, v110
	v_max_f32_e32 v111, v99, v99
	v_max_f32_e32 v112, v98, v98
	v_max_f32_e32 v111, v112, v111
	v_max_f32_e32 v112, v95, v95
	v_max_f32_e32 v113, v94, v94
	v_max_f32_e32 v112, v113, v112
	v_max3_f32 v112, v92, v93, v112
	v_max3_f32 v110, v110, v111, v112
	v_max_f32_e32 v111, v75, v75
	v_max_f32_e32 v112, v74, v74
	v_max_f32_e32 v111, v112, v111
	v_max_f32_e32 v112, v7, v7
	v_max_f32_e32 v113, v6, v6
	v_max_f32_e32 v112, v113, v112
	v_max3_f32 v111, v72, v73, v111
	v_max3_f32 v112, v4, v5, v112
	ds_bpermute_b32 v109, v173, v108
	v_max3_f32 v110, v110, v111, v112
	ds_bpermute_b32 v111, v173, v110
	s_waitcnt lgkmcnt(1)
	v_max_f32_e32 v109, v109, v109
	v_max_f32_e32 v108, v108, v109
	s_waitcnt lgkmcnt(0)
	v_max_f32_e32 v111, v111, v111
	ds_bpermute_b32 v109, v172, v108
	v_max_f32_e32 v110, v110, v111
	ds_bpermute_b32 v111, v172, v110
	s_waitcnt lgkmcnt(1)
	v_max_f32_e32 v109, v109, v109
	v_max_f32_e32 v109, v108, v109
	s_waitcnt lgkmcnt(0)
	v_max_f32_e32 v108, v111, v111
	v_max_f32_e32 v108, v110, v108
	v_max_f32_e32 v110, v109, v108
	v_cmp_lt_f32_e32 vcc, s36, v110
	s_cbranch_vccz .LBB0_1350
	v_max_f32_e32 v109, v109, v109
	v_max_f32_e32 v109, 0, v109
	v_max_f32_e32 v108, v108, v108
	v_sub_f32_e32 v104, v104, v109
	v_sub_f32_e32 v105, v105, v109
	v_sub_f32_e32 v106, v106, v109
	v_sub_f32_e32 v107, v107, v109
	v_sub_f32_e32 v100, v100, v109
	v_sub_f32_e32 v101, v101, v109
	v_sub_f32_e32 v102, v102, v109
	v_sub_f32_e32 v103, v103, v109
	v_sub_f32_e32 v84, v84, v109
	v_sub_f32_e32 v85, v85, v109
	v_sub_f32_e32 v86, v86, v109
	v_sub_f32_e32 v87, v87, v109
	v_sub_f32_e32 v8, v8, v109
	v_exp_f32_e64 v110, -v109
	v_sub_f32_e32 v9, v9, v109
	v_sub_f32_e32 v10, v10, v109
	v_sub_f32_e32 v11, v11, v109
	v_max_f32_e32 v109, 0, v108
	v_exp_f32_e64 v108, -v109
	v_pk_mul_f32 v[70:71], v[70:71], v[110:111] op_sel_hi:[1,0]
	v_pk_mul_f32 v[68:69], v[68:69], v[110:111] op_sel_hi:[1,0]
	v_pk_mul_f32 v[62:63], v[62:63], v[110:111] op_sel_hi:[1,0]
	v_pk_mul_f32 v[60:61], v[60:61], v[110:111] op_sel_hi:[1,0]
	v_pk_mul_f32 v[54:55], v[54:55], v[110:111] op_sel_hi:[1,0]
	v_pk_mul_f32 v[52:53], v[52:53], v[110:111] op_sel_hi:[1,0]
	v_pk_mul_f32 v[46:47], v[46:47], v[110:111] op_sel_hi:[1,0]
	v_pk_mul_f32 v[44:45], v[44:45], v[110:111] op_sel_hi:[1,0]
	v_pk_mul_f32 v[38:39], v[38:39], v[110:111] op_sel_hi:[1,0]
	v_pk_mul_f32 v[36:37], v[36:37], v[110:111] op_sel_hi:[1,0]
	v_sub_f32_e32 v96, v96, v109
	v_sub_f32_e32 v97, v97, v109
	v_sub_f32_e32 v98, v98, v109
	v_sub_f32_e32 v99, v99, v109
	v_sub_f32_e32 v92, v92, v109
	v_sub_f32_e32 v93, v93, v109
	v_sub_f32_e32 v94, v94, v109
	v_sub_f32_e32 v95, v95, v109
	v_sub_f32_e32 v72, v72, v109
	v_sub_f32_e32 v73, v73, v109
	v_sub_f32_e32 v74, v74, v109
	v_sub_f32_e32 v75, v75, v109
	v_sub_f32_e32 v4, v4, v109
	v_sub_f32_e32 v5, v5, v109
	v_sub_f32_e32 v6, v6, v109
	v_sub_f32_e32 v7, v7, v109
	v_pk_mul_f32 v[66:67], v[66:67], v[108:109] op_sel_hi:[1,0]
	v_pk_mul_f32 v[64:65], v[64:65], v[108:109] op_sel_hi:[1,0]
	v_pk_mul_f32 v[58:59], v[58:59], v[108:109] op_sel_hi:[1,0]
	v_pk_mul_f32 v[56:57], v[56:57], v[108:109] op_sel_hi:[1,0]
	v_pk_mul_f32 v[50:51], v[50:51], v[108:109] op_sel_hi:[1,0]
	v_pk_mul_f32 v[48:49], v[48:49], v[108:109] op_sel_hi:[1,0]
	v_pk_mul_f32 v[42:43], v[42:43], v[108:109] op_sel_hi:[1,0]
	v_pk_mul_f32 v[40:41], v[40:41], v[108:109] op_sel_hi:[1,0]
	v_pk_mul_f32 v[34:35], v[34:35], v[108:109] op_sel_hi:[1,0]
	v_pk_mul_f32 v[32:33], v[32:33], v[108:109] op_sel_hi:[1,0]
	s_branch .LBB0_1350
